# adds counted vmcnt waits in the GLA chunk loop (prefetched loads no longer drained with the stores) and reverses the w_out GEMM row-panel order too
# speedup vs baseline: 1.0065x; 1.0021x over previous
.LBB0_394:
	s_xor_b64 s[0:1], s[40:41], -1
	v_writelane_b32 v255, s0, 63
	v_or_b32_e32 v2, s8, v135
	s_lshl_b64 s[8:9], s[42:43], 2
	v_writelane_b32 v254, s1, 0
	v_lshlrev_b32_e32 v215, 2, v2
	s_add_u32 s0, s24, s8
	v_cndmask_b32_e64 v2, 0, 1, s[84:85]
	v_cndmask_b32_e64 v3, 0, 1, s[46:47]
	s_addc_u32 s1, s25, s9
	v_cndmask_b32_e64 v4, v2, v3, s[52:53]
	v_writelane_b32 v254, s0, 1
	v_and_b32_e32 v4, 1, v4
	v_readlane_b32 s8, v255, 22
	v_writelane_b32 v254, s1, 2
	v_cmp_eq_u32_e64 s[0:1], 1, v4
	v_cndmask_b32_e64 v4, 0, 1, s[48:49]
	v_cndmask_b32_e64 v5, v2, v4, s[52:53]
	v_and_b32_e32 v5, 1, v5
	v_cmp_eq_u32_e64 s[90:91], 1, v5
	v_cndmask_b32_e64 v5, 0, 1, s[50:51]
	v_cndmask_b32_e64 v6, v2, v5, s[52:53]
	v_and_b32_e32 v6, 1, v6
	v_cmp_eq_u32_e64 s[94:95], 1, v6
	v_cndmask_b32_e64 v6, 0, 1, s[44:45]
	v_writelane_b32 v254, s0, 3
	v_cndmask_b32_e64 v2, v2, v6, s[52:53]
	v_and_b32_e32 v2, 1, v2
	v_writelane_b32 v254, s1, 4
	v_readlane_b32 s0, v255, 18
	v_cmp_eq_u32_e64 s[42:43], 1, v2
	v_cndmask_b32_e64 v2, 0, 1, s[38:39]
	v_readlane_b32 s1, v255, 19
	v_readlane_b32 s9, v255, 23
	v_cndmask_b32_e64 v216, 0, 1, s[4:5]
	v_cndmask_b32_e64 v7, v2, v3, s[0:1]
	v_and_b32_e32 v7, 1, v7
	v_cmp_eq_u32_e64 s[80:81], 1, v7
	v_cndmask_b32_e64 v7, v2, v4, s[0:1]
	v_and_b32_e32 v7, 1, v7
	v_cmp_eq_u32_e64 s[24:25], 1, v7
	v_cndmask_b32_e64 v7, v2, v5, s[0:1]
	v_cndmask_b32_e64 v2, v2, v6, s[0:1]
	v_and_b32_e32 v2, 1, v2
	v_and_b32_e32 v7, 1, v7
	v_cmp_eq_u32_e64 s[46:47], 1, v2
	v_cndmask_b32_e64 v2, 0, 1, s[86:87]
	v_cmp_eq_u32_e64 s[40:41], 1, v7
	v_cndmask_b32_e64 v7, v2, v3, s[8:9]
	v_and_b32_e32 v7, 1, v7
	v_cmp_eq_u32_e64 s[0:1], 1, v7
	v_cndmask_b32_e64 v7, v2, v4, s[8:9]
	v_and_b32_e32 v7, 1, v7
	v_cmp_eq_u32_e64 s[64:65], 1, v7
	v_cndmask_b32_e64 v7, v2, v5, s[8:9]
	v_cndmask_b32_e64 v2, v2, v6, s[8:9]
	v_and_b32_e32 v2, 1, v2
	v_cmp_eq_u32_e64 s[68:69], 1, v2
	v_cndmask_b32_e64 v2, v3, v216, s[54:55]
	v_and_b32_e32 v2, 1, v2
	v_cmp_eq_u32_e64 s[70:71], 1, v2
	v_cndmask_b32_e64 v2, v4, v216, s[54:55]
	v_and_b32_e32 v2, 1, v2
	v_cmp_eq_u32_e64 s[72:73], 1, v2
	v_cndmask_b32_e64 v2, v5, v216, s[54:55]
	v_and_b32_e32 v2, 1, v2
	v_cmp_eq_u32_e64 s[74:75], 1, v2
	v_cndmask_b32_e64 v2, v6, v216, s[54:55]
	v_and_b32_e32 v7, 1, v7
	v_and_b32_e32 v2, 1, v2
	v_mov_b32_e32 v42, 0
	v_cmp_eq_u32_e64 s[66:67], 1, v7
	v_cmp_eq_u32_e64 s[76:77], 1, v2
	s_movk_i32 s44, 0x780
	s_mov_b32 s8, 30
	s_mov_b32 s9, 1
	v_mov_b32_e32 v43, v42
	v_mov_b32_e32 v44, v42
	v_mov_b32_e32 v45, v42
	v_mov_b32_e32 v46, v42
	v_mov_b32_e32 v47, v42
	v_mov_b32_e32 v48, v42
	v_mov_b32_e32 v49, v42
	v_mov_b32_e32 v50, v42
	v_mov_b32_e32 v51, v42
	v_mov_b32_e32 v52, v42
	v_mov_b32_e32 v53, v42
	v_mov_b32_e32 v54, v42
	v_mov_b32_e32 v55, v42
	v_mov_b32_e32 v56, v42
	v_mov_b32_e32 v57, v42
	s_waitcnt vmcnt(0) lgkmcnt(0)
	s_barrier
.LBB0_395:
	v_readlane_b32 s22, v255, 13
	v_mov_b32_e32 v66, s6
	s_mov_b32 s23, 0x800000
	v_mov_b32_e32 v2, s22
	ds_read_b128 v[58:61], v66 offset:63744
	ds_read_b128 v[6:9], v2
	ds_read_b128 v[2:5], v2 offset:16
	ds_read_b128 v[62:65], v66 offset:63760
	s_mov_b32 s22, 0xbfb8aa3b
	s_mov_b32 s45, 0x3f317217
	s_and_b64 s[100:101], s[92:93], exec
	s_cbranch_scc0 .Lgla_bwd_w
	s_waitcnt vmcnt(4) lgkmcnt(0)
	s_branch .Lgla_w_done
.Lgla_bwd_w:
	s_waitcnt vmcnt(12) lgkmcnt(0)
.Lgla_w_done:
	v_fma_f32 v6, v22, v58, v6
	v_fma_f32 v7, v22, v59, v7
	v_fma_f32 v8, v22, v60, v8
	v_fmac_f32_e32 v9, v22, v61
	ds_read_b128 v[58:61], v66 offset:64000
	v_fma_f32 v67, v22, v62, v2
	v_fma_f32 v3, v22, v63, v3
	v_fma_f32 v2, v22, v64, v4
	v_fmac_f32_e32 v5, v22, v65
	ds_read_b128 v[62:65], v66 offset:64016
	s_waitcnt lgkmcnt(1)
	v_fmac_f32_e32 v9, v23, v61
	v_fmac_f32_e32 v8, v23, v60
	v_fmac_f32_e32 v7, v23, v59
	v_fmac_f32_e32 v6, v23, v58
	ds_read_b128 v[58:61], v66 offset:64256
	s_waitcnt lgkmcnt(1)
	v_fmac_f32_e32 v5, v23, v65
	v_fmac_f32_e32 v2, v23, v64
	v_fmac_f32_e32 v3, v23, v63
	v_fmac_f32_e32 v67, v23, v62
	ds_read_b128 v[62:65], v66 offset:64272
	s_waitcnt lgkmcnt(1)
	v_fmac_f32_e32 v6, v24, v58
	v_fmac_f32_e32 v7, v24, v59
	v_fmac_f32_e32 v8, v24, v60
	v_fmac_f32_e32 v9, v24, v61
	ds_read_b128 v[58:61], v66 offset:64512
	s_waitcnt lgkmcnt(1)
	v_fmac_f32_e32 v67, v24, v62
	v_fmac_f32_e32 v3, v24, v63
	v_fmac_f32_e32 v2, v24, v64
	v_fmac_f32_e32 v5, v24, v65
	ds_read_b128 v[62:65], v66 offset:64528
	s_waitcnt lgkmcnt(1)
	v_fmac_f32_e32 v9, v25, v61
	v_fmac_f32_e32 v8, v25, v60
	v_fmac_f32_e32 v7, v25, v59
	v_fmac_f32_e32 v6, v25, v58
	ds_read_b128 v[58:61], v66 offset:64768
	s_waitcnt lgkmcnt(1)
	v_fmac_f32_e32 v5, v25, v65
	v_fmac_f32_e32 v2, v25, v64
	v_fmac_f32_e32 v3, v25, v63
	v_fmac_f32_e32 v67, v25, v62
	ds_read_b128 v[62:65], v66 offset:64784
	s_waitcnt lgkmcnt(1)
	v_fmac_f32_e32 v6, v18, v58
	v_fmac_f32_e32 v7, v18, v59
	v_fmac_f32_e32 v8, v18, v60
	v_fmac_f32_e32 v9, v18, v61
	ds_read_b128 v[58:61], v66 offset:65024
	s_waitcnt lgkmcnt(1)
	v_fmac_f32_e32 v67, v18, v62
	v_fmac_f32_e32 v3, v18, v63
	v_fmac_f32_e32 v2, v18, v64
	v_fmac_f32_e32 v5, v18, v65
	ds_read_b128 v[62:65], v66 offset:65040
	s_waitcnt lgkmcnt(1)
	v_fmac_f32_e32 v9, v19, v61
	v_fmac_f32_e32 v8, v19, v60
	v_fmac_f32_e32 v7, v19, v59
	v_fmac_f32_e32 v6, v19, v58
	ds_read_b128 v[58:61], v66 offset:65280
	v_mov_b32_e32 v4, s7
	s_waitcnt lgkmcnt(1)
	v_fmac_f32_e32 v5, v19, v65
	v_fmac_f32_e32 v2, v19, v64
	v_fmac_f32_e32 v3, v19, v63
	v_fmac_f32_e32 v67, v19, v62
	ds_read_b128 v[62:65], v66 offset:65296
	s_waitcnt lgkmcnt(1)
	v_fmac_f32_e32 v6, v20, v58
	v_fmac_f32_e32 v7, v20, v59
	v_fmac_f32_e32 v8, v20, v60
	v_fmac_f32_e32 v9, v20, v61
	ds_read_b128 v[58:61], v4 offset:1792
	s_waitcnt lgkmcnt(1)
	v_fmac_f32_e32 v67, v20, v62
	v_fmac_f32_e32 v3, v20, v63
	v_fmac_f32_e32 v2, v20, v64
	v_fmac_f32_e32 v5, v20, v65
	ds_read_b128 v[62:65], v4 offset:1808
	s_waitcnt lgkmcnt(1)
	v_fmac_f32_e32 v9, v21, v61
	v_fmac_f32_e32 v8, v21, v60
	v_fmac_f32_e32 v7, v21, v59
	v_fmac_f32_e32 v6, v21, v58
	ds_read_b128 v[58:61], v4 offset:2048
	s_waitcnt lgkmcnt(1)
	v_fmac_f32_e32 v5, v21, v65
	v_fmac_f32_e32 v2, v21, v64
	v_fmac_f32_e32 v3, v21, v63
	v_fmac_f32_e32 v67, v21, v62
	ds_read_b128 v[62:65], v4 offset:2064
	s_waitcnt lgkmcnt(1)
	v_fmac_f32_e32 v6, v14, v58
	v_fmac_f32_e32 v7, v14, v59
	v_fmac_f32_e32 v8, v14, v60
	v_fmac_f32_e32 v9, v14, v61
	ds_read_b128 v[58:61], v4 offset:2304
	s_waitcnt lgkmcnt(1)
	v_fmac_f32_e32 v67, v14, v62
	v_fmac_f32_e32 v3, v14, v63
	v_fmac_f32_e32 v2, v14, v64
	v_fmac_f32_e32 v5, v14, v65
	ds_read_b128 v[62:65], v4 offset:2320
	s_waitcnt lgkmcnt(1)
	v_fmac_f32_e32 v9, v15, v61
	v_fmac_f32_e32 v8, v15, v60
	v_fmac_f32_e32 v7, v15, v59
	v_fmac_f32_e32 v6, v15, v58
	ds_read_b128 v[58:61], v4 offset:2560
	s_waitcnt lgkmcnt(1)
	v_fmac_f32_e32 v5, v15, v65
	v_fmac_f32_e32 v2, v15, v64
	v_fmac_f32_e32 v3, v15, v63
	v_fmac_f32_e32 v67, v15, v62
	ds_read_b128 v[62:65], v4 offset:2576
	s_waitcnt lgkmcnt(1)
	v_fmac_f32_e32 v6, v16, v58
	v_fmac_f32_e32 v7, v16, v59
	v_fmac_f32_e32 v8, v16, v60
	v_fmac_f32_e32 v9, v16, v61
	ds_read_b128 v[58:61], v4 offset:2816
	s_waitcnt lgkmcnt(1)
	v_fmac_f32_e32 v67, v16, v62
	v_fmac_f32_e32 v3, v16, v63
	v_fmac_f32_e32 v2, v16, v64
	v_fmac_f32_e32 v5, v16, v65
	ds_read_b128 v[62:65], v4 offset:2832
	s_waitcnt lgkmcnt(1)
	v_fmac_f32_e32 v9, v17, v61
	v_fmac_f32_e32 v8, v17, v60
	v_fmac_f32_e32 v7, v17, v59
	v_fmac_f32_e32 v6, v17, v58
	ds_read_b128 v[58:61], v4 offset:3072
	s_waitcnt lgkmcnt(1)
	v_fmac_f32_e32 v5, v17, v65
	v_fmac_f32_e32 v2, v17, v64
	v_fmac_f32_e32 v3, v17, v63
	v_fmac_f32_e32 v67, v17, v62
	ds_read_b128 v[62:65], v4 offset:3088
	s_waitcnt lgkmcnt(1)
	v_fmac_f32_e32 v6, v10, v58
	v_fmac_f32_e32 v7, v10, v59
	v_fmac_f32_e32 v8, v10, v60
	v_fmac_f32_e32 v9, v10, v61
	ds_read_b128 v[58:61], v4 offset:3328
	s_waitcnt lgkmcnt(1)
	v_fmac_f32_e32 v67, v10, v62
	v_fmac_f32_e32 v3, v10, v63
	v_fmac_f32_e32 v2, v10, v64
	v_fmac_f32_e32 v5, v10, v65
	ds_read_b128 v[62:65], v4 offset:3344
	s_waitcnt lgkmcnt(1)
	v_fmac_f32_e32 v9, v11, v61
	v_fmac_f32_e32 v8, v11, v60
	v_fmac_f32_e32 v7, v11, v59
	v_fmac_f32_e32 v6, v11, v58
	ds_read_b128 v[58:61], v4 offset:3584
	s_waitcnt lgkmcnt(1)
	v_fmac_f32_e32 v5, v11, v65
	v_fmac_f32_e32 v2, v11, v64
	v_fmac_f32_e32 v3, v11, v63
	v_fmac_f32_e32 v67, v11, v62
	ds_read_b128 v[62:65], v4 offset:3600
	s_waitcnt lgkmcnt(1)
	v_fmac_f32_e32 v6, v12, v58
	v_fmac_f32_e32 v7, v12, v59
	v_fmac_f32_e32 v8, v12, v60
	v_fmac_f32_e32 v9, v12, v61
	ds_read_b128 v[58:61], v4 offset:3840
	s_waitcnt lgkmcnt(1)
	v_fmac_f32_e32 v67, v12, v62
	v_fmac_f32_e32 v3, v12, v63
	v_fmac_f32_e32 v2, v12, v64
	v_fmac_f32_e32 v5, v12, v65
	ds_read_b128 v[62:65], v4 offset:3856
	s_waitcnt lgkmcnt(1)
	v_fmac_f32_e32 v6, v13, v58
	v_mul_f32_e64 v4, |v6|, s22
	v_exp_f32_e32 v4, v4
	v_fmac_f32_e32 v7, v13, v59
	s_waitcnt lgkmcnt(0)
	v_fmac_f32_e32 v67, v13, v62
	v_mul_f32_e64 v59, |v67|, s22
	v_add_f32_e32 v4, 1.0, v4
	v_cmp_gt_f32_e32 vcc, s23, v4
	v_exp_f32_e32 v59, v59
	s_mov_b32 s48, 0x7f800000
	v_cndmask_b32_e64 v58, 0, 32, vcc
	v_ldexp_f32 v4, v4, v58
	v_log_f32_e32 v4, v4
	v_min_f32_e32 v6, 0, v6
	v_fmac_f32_e32 v8, v13, v60
	v_mul_f32_e64 v60, |v7|, s22
	v_mul_f32_e32 v58, 0x3f317217, v4
	v_fma_f32 v58, v4, s45, -v58
	v_fmac_f32_e32 v58, 0x3377d1cf, v4
	v_fmac_f32_e32 v58, 0x3f317217, v4
	v_cmp_lt_f32_e64 s[78:79], |v4|, s48
	v_exp_f32_e32 v60, v60
	v_fmac_f32_e32 v3, v13, v63
	v_cndmask_b32_e64 v4, v4, v58, s[78:79]
	v_cndmask_b32_e32 v58, 0, v235, vcc
	v_sub_f32_e32 v4, v4, v58
	v_add_f32_e32 v58, 1.0, v59
	v_cmp_gt_f32_e32 vcc, s23, v58
	v_sub_f32_e32 v4, v6, v4
	v_fmac_f32_e32 v2, v13, v64
	v_cndmask_b32_e64 v59, 0, 32, vcc
	v_ldexp_f32 v58, v58, v59
	v_log_f32_e32 v59, v58
	v_mul_f32_e32 v58, 0x3d800000, v4
	v_min_f32_e32 v4, 0, v67
	v_fmac_f32_e32 v9, v13, v61
	v_mul_f32_e32 v6, 0x3f317217, v59
	v_fma_f32 v6, v59, s45, -v6
	v_fmac_f32_e32 v6, 0x3377d1cf, v59
	v_fmac_f32_e32 v6, 0x3f317217, v59
	v_cmp_lt_f32_e64 s[78:79], |v59|, s48
	v_fmac_f32_e32 v5, v13, v65
	s_nop 0
	v_cndmask_b32_e64 v6, v59, v6, s[78:79]
	v_cndmask_b32_e32 v59, 0, v235, vcc
	v_sub_f32_e32 v6, v6, v59
	v_add_f32_e32 v59, 1.0, v60
	v_cmp_gt_f32_e32 vcc, s23, v59
	v_sub_f32_e32 v4, v4, v6
	s_nop 0
	v_cndmask_b32_e64 v60, 0, 32, vcc
	v_ldexp_f32 v59, v59, v60
	v_log_f32_e32 v60, v59
	v_mul_f32_e32 v59, 0x3d800000, v4
	v_min_f32_e32 v4, 0, v7
	v_mul_f32_e64 v7, |v3|, s22
	v_exp_f32_e32 v7, v7
	v_mul_f32_e32 v6, 0x3f317217, v60
	v_fma_f32 v6, v60, s45, -v6
	v_fmac_f32_e32 v6, 0x3377d1cf, v60
	v_fmac_f32_e32 v6, 0x3f317217, v60
	v_cmp_lt_f32_e64 s[78:79], |v60|, s48
	v_add_f32_e32 v7, 1.0, v7
	v_min_f32_e32 v3, 0, v3
	v_cndmask_b32_e64 v6, v60, v6, s[78:79]
	v_cndmask_b32_e32 v60, 0, v235, vcc
	v_cmp_gt_f32_e32 vcc, s23, v7
	v_sub_f32_e32 v6, v6, v60
	v_sub_f32_e32 v4, v4, v6
	v_cndmask_b32_e64 v60, 0, 32, vcc
	v_ldexp_f32 v7, v7, v60
	v_log_f32_e32 v7, v7
	v_mul_f32_e64 v6, |v8|, s22
	v_exp_f32_e32 v6, v6
	v_mul_f32_e32 v60, 0x3d800000, v4
	v_mul_f32_e32 v4, 0x3f317217, v7
	v_fma_f32 v4, v7, s45, -v4
	v_fmac_f32_e32 v4, 0x3377d1cf, v7
	v_fmac_f32_e32 v4, 0x3f317217, v7
	v_cmp_lt_f32_e64 s[78:79], |v7|, s48
	v_add_f32_e32 v6, 1.0, v6
	s_nop 0
	v_cndmask_b32_e64 v4, v7, v4, s[78:79]
	v_cndmask_b32_e32 v7, 0, v235, vcc
	v_cmp_gt_f32_e32 vcc, s23, v6
	v_sub_f32_e32 v4, v4, v7
	v_sub_f32_e32 v3, v3, v4
	v_cndmask_b32_e64 v7, 0, 32, vcc
	v_ldexp_f32 v6, v6, v7
	v_log_f32_e32 v6, v6
	v_mul_f32_e64 v7, |v2|, s22
	v_exp_f32_e32 v7, v7
	v_mul_f32_e32 v61, 0x3d800000, v3
	v_mul_f32_e32 v4, 0x3f317217, v6
	v_fma_f32 v4, v6, s45, -v4
	v_fmac_f32_e32 v4, 0x3377d1cf, v6
	v_fmac_f32_e32 v4, 0x3f317217, v6
	v_cmp_lt_f32_e64 s[78:79], |v6|, s48
	v_min_f32_e32 v3, 0, v8
	v_min_f32_e32 v2, 0, v2
	v_cndmask_b32_e64 v4, v6, v4, s[78:79]
	v_cndmask_b32_e32 v6, 0, v235, vcc
	v_sub_f32_e32 v4, v4, v6
	v_add_f32_e32 v6, 1.0, v7
	v_cmp_gt_f32_e32 vcc, s23, v6
	v_sub_f32_e32 v3, v3, v4
	v_mul_f32_e64 v4, |v9|, s22
	v_cndmask_b32_e64 v7, 0, 32, vcc
	v_ldexp_f32 v6, v6, v7
	v_log_f32_e32 v6, v6
	v_exp_f32_e32 v4, v4
	v_mul_f32_e32 v62, 0x3d800000, v3
	v_mul_f32_e32 v3, 0x3f317217, v6
	v_fma_f32 v3, v6, s45, -v3
	v_fmac_f32_e32 v3, 0x3377d1cf, v6
	v_fmac_f32_e32 v3, 0x3f317217, v6
	v_cmp_lt_f32_e64 s[78:79], |v6|, s48
	v_add_f32_e32 v4, 1.0, v4
	s_nop 0
	v_cndmask_b32_e64 v3, v6, v3, s[78:79]
	v_cndmask_b32_e32 v6, 0, v235, vcc
	v_cmp_gt_f32_e32 vcc, s23, v4
	v_sub_f32_e32 v3, v3, v6
	v_sub_f32_e32 v2, v2, v3
	v_cndmask_b32_e64 v6, 0, 32, vcc
	v_ldexp_f32 v4, v4, v6
	v_log_f32_e32 v4, v4
	v_mul_f32_e64 v6, |v5|, s22
	v_exp_f32_e32 v6, v6
	v_mul_f32_e32 v63, 0x3d800000, v2
	v_mul_f32_e32 v3, 0x3f317217, v4
	v_fma_f32 v3, v4, s45, -v3
	v_fmac_f32_e32 v3, 0x3377d1cf, v4
	v_fmac_f32_e32 v3, 0x3f317217, v4
	v_cmp_lt_f32_e64 s[78:79], |v4|, s48
	v_min_f32_e32 v2, 0, v9
	s_nop 0
	v_cndmask_b32_e64 v3, v4, v3, s[78:79]
	v_cndmask_b32_e32 v4, 0, v235, vcc
	v_sub_f32_e32 v3, v3, v4
	v_add_f32_e32 v4, 1.0, v6
	v_cmp_gt_f32_e32 vcc, s23, v4
	v_sub_f32_e32 v2, v2, v3
	v_mul_f32_e32 v64, 0x3d800000, v2
	v_cndmask_b32_e64 v6, 0, 32, vcc
	v_ldexp_f32 v4, v4, v6
	v_log_f32_e32 v4, v4
	v_min_f32_e32 v2, 0, v5
	s_mov_b64 s[22:23], -1
	v_mul_f32_e32 v3, 0x3f317217, v4
	v_fma_f32 v3, v4, s45, -v3
	v_fmac_f32_e32 v3, 0x3377d1cf, v4
	v_fmac_f32_e32 v3, 0x3f317217, v4
	v_cmp_lt_f32_e64 s[78:79], |v4|, s48
	s_nop 1
	v_cndmask_b32_e64 v3, v4, v3, s[78:79]
	v_cndmask_b32_e32 v4, 0, v235, vcc
	v_sub_f32_e32 v3, v3, v4
	v_sub_f32_e32 v2, v2, v3
	v_mul_f32_e32 v65, 0x3d800000, v2
	v_cmp_ne_u32_e64 s[78:79], 1, v216
	s_andn2_b64 vcc, exec, s[4:5]
	s_cbranch_vccnz .LBB0_397
	ds_bpermute_b32 v2, v182, v58
	ds_bpermute_b32 v3, v182, v60
	ds_bpermute_b32 v4, v182, v62
	ds_bpermute_b32 v5, v182, v64
	ds_bpermute_b32 v6, v182, v59
	ds_bpermute_b32 v7, v182, v61
	ds_bpermute_b32 v8, v182, v63
	ds_bpermute_b32 v9, v182, v65
	s_waitcnt lgkmcnt(7)
	v_add_f32_e32 v2, v58, v2
	s_waitcnt lgkmcnt(6)
	v_add_f32_e32 v3, v60, v3
	s_waitcnt lgkmcnt(5)
	v_add_f32_e32 v4, v62, v4
	s_waitcnt lgkmcnt(4)
	v_add_f32_e32 v5, v64, v5
	s_waitcnt lgkmcnt(3)
	v_add_f32_e32 v6, v59, v6
	s_waitcnt lgkmcnt(2)
	v_add_f32_e32 v7, v61, v7
	s_waitcnt lgkmcnt(1)
	v_add_f32_e32 v8, v63, v8
	s_waitcnt lgkmcnt(0)
	v_add_f32_e32 v9, v65, v9
	v_cndmask_b32_e64 v9, v9, v65, s[14:15]
	v_cndmask_b32_e64 v8, v8, v63, s[14:15]
	v_cndmask_b32_e64 v7, v7, v61, s[14:15]
	v_cndmask_b32_e64 v4, v4, v62, s[14:15]
	v_cndmask_b32_e64 v3, v3, v60, s[14:15]
	v_cndmask_b32_e64 v2, v2, v58, s[14:15]
	v_cndmask_b32_e64 v6, v6, v59, s[14:15]
	v_cndmask_b32_e64 v5, v5, v64, s[14:15]
	ds_bpermute_b32 v66, v183, v2
	ds_bpermute_b32 v67, v183, v3
	ds_bpermute_b32 v68, v183, v4
	ds_bpermute_b32 v69, v183, v5
	ds_bpermute_b32 v70, v183, v6
	ds_bpermute_b32 v71, v183, v7
	ds_bpermute_b32 v72, v183, v8
	ds_bpermute_b32 v73, v183, v9
	s_waitcnt lgkmcnt(7)
	v_add_f32_e32 v66, v2, v66
	s_waitcnt lgkmcnt(6)
	v_add_f32_e32 v67, v3, v67
	s_waitcnt lgkmcnt(5)
	v_add_f32_e32 v68, v4, v68
	s_waitcnt lgkmcnt(4)
	v_add_f32_e32 v69, v5, v69
	s_waitcnt lgkmcnt(3)
	v_add_f32_e32 v70, v6, v70
	s_waitcnt lgkmcnt(2)
	v_add_f32_e32 v71, v7, v71
	s_waitcnt lgkmcnt(1)
	v_add_f32_e32 v72, v8, v72
	s_waitcnt lgkmcnt(0)
	v_add_f32_e32 v73, v9, v73
	v_cndmask_b32_e64 v9, v9, v73, s[16:17]
	v_cndmask_b32_e64 v8, v8, v72, s[16:17]
	v_cndmask_b32_e64 v7, v7, v71, s[16:17]
	v_cndmask_b32_e64 v4, v4, v68, s[16:17]
	v_cndmask_b32_e64 v3, v3, v67, s[16:17]
	v_cndmask_b32_e64 v2, v2, v66, s[16:17]
	v_cndmask_b32_e64 v6, v6, v70, s[16:17]
	v_cndmask_b32_e64 v5, v5, v69, s[16:17]
	ds_bpermute_b32 v66, v184, v2
	ds_bpermute_b32 v67, v184, v3
	ds_bpermute_b32 v68, v184, v4
	ds_bpermute_b32 v69, v184, v5
	ds_bpermute_b32 v70, v184, v6
	ds_bpermute_b32 v71, v184, v7
	ds_bpermute_b32 v72, v184, v8
	ds_bpermute_b32 v73, v184, v9
	s_waitcnt lgkmcnt(7)
	v_add_f32_e32 v66, v2, v66
	s_waitcnt lgkmcnt(6)
	v_add_f32_e32 v67, v3, v67
	s_waitcnt lgkmcnt(5)
	v_add_f32_e32 v68, v4, v68
	s_waitcnt lgkmcnt(4)
	v_add_f32_e32 v69, v5, v69
	s_waitcnt lgkmcnt(3)
	v_add_f32_e32 v70, v6, v70
	s_waitcnt lgkmcnt(2)
	v_add_f32_e32 v71, v7, v71
	s_waitcnt lgkmcnt(1)
	v_add_f32_e32 v72, v8, v72
	s_waitcnt lgkmcnt(0)
	v_add_f32_e32 v73, v9, v73
	v_cndmask_b32_e64 v9, v9, v73, s[18:19]
	v_cndmask_b32_e64 v8, v8, v72, s[18:19]
	v_cndmask_b32_e64 v7, v7, v71, s[18:19]
	v_cndmask_b32_e64 v4, v4, v68, s[18:19]
	v_cndmask_b32_e64 v3, v3, v67, s[18:19]
	v_cndmask_b32_e64 v2, v2, v66, s[18:19]
	v_cndmask_b32_e64 v6, v6, v70, s[18:19]
	v_cndmask_b32_e64 v5, v5, v69, s[18:19]
	ds_bpermute_b32 v66, v185, v2
	ds_bpermute_b32 v67, v185, v3
	ds_bpermute_b32 v68, v185, v4
	ds_bpermute_b32 v69, v185, v5
	ds_bpermute_b32 v70, v185, v6
	ds_bpermute_b32 v71, v185, v7
	ds_bpermute_b32 v72, v185, v8
	ds_bpermute_b32 v73, v185, v9
	s_waitcnt lgkmcnt(7)
	v_add_f32_e32 v66, v2, v66
	s_waitcnt lgkmcnt(6)
	v_add_f32_e32 v67, v3, v67
	s_waitcnt lgkmcnt(5)
	v_add_f32_e32 v68, v4, v68
	s_waitcnt lgkmcnt(4)
	v_add_f32_e32 v69, v5, v69
	s_waitcnt lgkmcnt(3)
	v_add_f32_e32 v70, v6, v70
	s_waitcnt lgkmcnt(2)
	v_add_f32_e32 v71, v7, v71
	s_waitcnt lgkmcnt(1)
	v_add_f32_e32 v72, v8, v72
	s_waitcnt lgkmcnt(0)
	v_add_f32_e32 v73, v9, v73
	v_cndmask_b32_e64 v9, v9, v73, s[20:21]
	v_cndmask_b32_e64 v8, v8, v72, s[20:21]
	v_cndmask_b32_e64 v7, v7, v71, s[20:21]
	v_cndmask_b32_e64 v4, v4, v68, s[20:21]
	v_cndmask_b32_e64 v3, v3, v67, s[20:21]
	v_cndmask_b32_e64 v2, v2, v66, s[20:21]
	v_cndmask_b32_e64 v6, v6, v70, s[20:21]
	v_cndmask_b32_e64 v5, v5, v69, s[20:21]
	ds_bpermute_b32 v66, v186, v2
	ds_bpermute_b32 v67, v186, v3
	ds_bpermute_b32 v68, v186, v4
	ds_bpermute_b32 v69, v186, v5
	ds_bpermute_b32 v70, v186, v6
	ds_bpermute_b32 v71, v186, v7
	ds_bpermute_b32 v72, v186, v8
	ds_bpermute_b32 v73, v186, v9
	s_waitcnt lgkmcnt(7)
	v_add_f32_e32 v66, v2, v66
	s_waitcnt lgkmcnt(6)
	v_add_f32_e32 v67, v3, v67
	s_waitcnt lgkmcnt(5)
	v_add_f32_e32 v68, v4, v68
	s_waitcnt lgkmcnt(4)
	v_add_f32_e32 v69, v5, v69
	s_waitcnt lgkmcnt(3)
	v_add_f32_e32 v70, v6, v70
	s_waitcnt lgkmcnt(2)
	v_add_f32_e32 v71, v7, v71
	s_waitcnt lgkmcnt(1)
	v_add_f32_e32 v72, v8, v72
	s_waitcnt lgkmcnt(0)
	v_add_f32_e32 v73, v9, v73
	v_cndmask_b32_e64 v9, v9, v73, s[26:27]
	v_cndmask_b32_e64 v8, v8, v72, s[26:27]
	v_cndmask_b32_e64 v7, v7, v71, s[26:27]
	v_cndmask_b32_e64 v4, v4, v68, s[26:27]
	v_cndmask_b32_e64 v3, v3, v67, s[26:27]
	v_cndmask_b32_e64 v2, v2, v66, s[26:27]
	v_cndmask_b32_e64 v6, v6, v70, s[26:27]
	v_cndmask_b32_e64 v5, v5, v69, s[26:27]
	ds_bpermute_b32 v66, v234, v2
	ds_bpermute_b32 v67, v234, v3
	ds_bpermute_b32 v68, v234, v4
	ds_bpermute_b32 v69, v234, v5
	ds_bpermute_b32 v70, v234, v6
	ds_bpermute_b32 v71, v234, v7
	ds_bpermute_b32 v72, v234, v8
	ds_bpermute_b32 v73, v234, v9
	s_waitcnt lgkmcnt(7)
	v_add_f32_e32 v66, v2, v66
	s_waitcnt lgkmcnt(6)
	v_add_f32_e32 v67, v3, v67
	s_waitcnt lgkmcnt(5)
	v_add_f32_e32 v68, v4, v68
	s_waitcnt lgkmcnt(4)
	v_add_f32_e32 v69, v5, v69
	s_waitcnt lgkmcnt(3)
	v_add_f32_e32 v70, v6, v70
	s_waitcnt lgkmcnt(2)
	v_add_f32_e32 v71, v7, v71
	s_waitcnt lgkmcnt(1)
	v_add_f32_e32 v72, v8, v72
	s_waitcnt lgkmcnt(0)
	v_add_f32_e32 v73, v9, v73
	v_cndmask_b32_e64 v2, v2, v66, s[28:29]
	v_cndmask_b32_e64 v9, v9, v73, s[28:29]
	v_cndmask_b32_e64 v8, v8, v72, s[28:29]
	v_cndmask_b32_e64 v7, v7, v71, s[28:29]
	v_cndmask_b32_e64 v6, v6, v70, s[28:29]
	v_cndmask_b32_e64 v5, v5, v69, s[28:29]
	v_cndmask_b32_e64 v4, v4, v68, s[28:29]
	v_cndmask_b32_e64 v3, v3, v67, s[28:29]
	s_mov_b64 s[22:23], 0

.LBB0_401:
	s_or_b64 exec, exec, s[22:23]
	s_cmp_lg_u32 s8, -1
	s_cselect_b64 s[82:83], -1, 0
	s_cmp_eq_u32 s8, -1
	ds_write_b128 v200, v[34:37] offset:27648
	ds_write_b128 v200, v[38:41] offset:36352
	s_waitcnt lgkmcnt(0)
	s_barrier
	s_waitcnt vmcnt(0)
	s_cbranch_scc1 .LBB0_403
	s_and_b64 s[22:23], s[92:93], exec
	s_cselect_b32 s22, s9, s8
	s_lshl_b32 s22, s22, 6
	s_ashr_i32 s23, s22, 31
	s_add_u32 s22, s88, s22
	s_addc_u32 s23, s89, s23
	v_mov_b32_e32 v3, s23
	v_or_b32_e32 v2, s22, v134
	v_readlane_b32 s48, v254, 1
	v_lshlrev_b64 v[4:5], 7, v[2:3]
	v_readlane_b32 s49, v254, 2
	s_movk_i32 s97, 0x2400
	s_movk_i32 s45, 0x1000
	v_lshl_add_u64 v[4:5], s[48:49], 0, v[4:5]
	v_readlane_b32 s48, v253, 31
	v_readlane_b32 s49, v253, 32
	global_load_dwordx4 v[10:13], v[4:5], off offset:48
	global_load_dwordx4 v[14:17], v[4:5], off offset:32
	global_load_dwordx4 v[18:21], v[4:5], off offset:16
	global_load_dwordx4 v[22:25], v[4:5], off
	v_mov_b64_e32 v[4:5], s[48:49]
	v_readlane_b32 s48, v255, 47
	v_mad_u64_u32 v[2:3], vcc, v2, s97, v[4:5]
	v_readlane_b32 s50, v255, 49
	v_readlane_b32 s51, v255, 50
	v_mad_i32_i24 v3, s23, v232, v3
	v_readlane_b32 s49, v255, 48
	v_readlane_b32 s50, v255, 11
	v_readlane_b32 s51, v255, 12
	v_lshl_add_u64 v[2:3], v[2:3], 0, s[48:49]
	v_readlane_b32 s52, v255, 51
	v_lshl_add_u64 v[2:3], s[50:51], 1, v[2:3]
	v_add_co_u32_e32 v2, vcc, s45, v2
	v_readlane_b32 s53, v255, 52
	s_nop 0
	v_addc_co_u32_e32 v3, vcc, 0, v3, vcc
	global_load_dwordx4 v[26:29], v[2:3], off offset:2048
	global_load_dwordx4 v[30:33], v[2:3], off offset:2560
	v_lshl_add_u64 v[2:3], s[22:23], 0, v[136:137]
	v_mad_u64_u32 v[4:5], s[22:23], v2, s97, v[4:5]
	v_mad_i32_i24 v5, v3, s97, v5
	s_mov_b32 s97, s49
	v_lshl_add_u64 v[2:3], v[4:5], 0, s[96:97]
	v_lshl_add_u64 v[2:3], v[2:3], 0, v[202:203]
	v_add_co_u32_e32 v4, vcc, 0x1000, v2
	v_readlane_b32 s54, v255, 53
	s_nop 0
	v_addc_co_u32_e32 v5, vcc, 0, v3, vcc
	v_add_co_u32_e32 v2, vcc, 0x49000, v2
	v_readlane_b32 s55, v255, 54
	s_nop 0
	v_addc_co_u32_e32 v3, vcc, 0, v3, vcc
	global_load_dwordx4 v[34:37], v[4:5], off offset:3072
	global_load_dwordx4 v[38:41], v[2:3], off offset:3072
	v_readlane_b32 s56, v255, 55
	v_readlane_b32 s57, v255, 56
	v_readlane_b32 s58, v255, 57
	v_readlane_b32 s59, v255, 58
	v_readlane_b32 s60, v255, 59
	v_readlane_b32 s61, v255, 60
	v_readlane_b32 s62, v255, 61
	v_readlane_b32 s63, v255, 62

.LBB0_607:
	s_or_b64 exec, exec, s[0:1]
	v_readlane_b32 s0, v253, 2
	v_readlane_b32 s14, v253, 0
	s_mov_b32 s12, s65
	v_readlane_b32 s15, v253, 1
	v_readlane_b32 s1, v253, 3
	v_mov_b32_e32 v3, v0
	s_waitcnt lgkmcnt(0)
	s_barrier
	s_cmpk_gt_i32 s14, 0x5ff
	v_readfirstlane_b32 s10, v3
	s_cbranch_scc1 .LBB0_623
	v_bfe_i32 v4, v3, 27, 1
	v_lshlrev_b32_e32 v6, 4, v3
	v_lshrrev_b32_e32 v4, 22, v4
	v_add_u32_e32 v4, v6, v4
	v_and_b32_e32 v4, 0xfffffc00, v4
	v_sub_u32_e32 v4, v6, v4
	v_lshrrev_b32_e32 v5, 4, v4
	v_bitop3_b32 v5, v5, v4, 32 bitop3:0x6c
	v_ashrrev_i32_e32 v4, 31, v4
	v_lshrrev_b32_e32 v4, 26, v4
	v_ashrrev_i32_e32 v2, 31, v3
	v_add_u32_e32 v4, v5, v4
	v_lshrrev_b32_e32 v2, 26, v2
	v_ashrrev_i32_e32 v4, 6, v4
	v_add_u32_e32 v2, v3, v2
	v_mul_i32_i24_e32 v9, 64, v4
	v_ashrrev_i32_e32 v2, 6, v2
	v_sub_u32_e32 v5, v5, v9
	v_lshlrev_b32_e32 v7, 3, v2
	v_lshlrev_b32_e32 v8, 5, v2
	v_ashrrev_i16_sdwa v5, v1, sext(v5) dst_sel:DWORD dst_unused:UNUSED_PAD src0_sel:DWORD src1_sel:BYTE_0
	v_and_b32_e32 v7, -16, v7
	v_and_b32_e32 v8, 32, v8
	v_bfe_i32 v5, v5, 0, 16
	v_add_u32_e32 v7, v4, v7
	s_waitcnt vmcnt(0)
	v_and_b32_e32 v11, 3, v4
	s_mov_b32 s6, 0xfffe0
	v_add_lshl_u32 v8, v8, v5, 1
	v_lshlrev_b32_e32 v9, 1, v7
	v_lshrrev_b32_e32 v10, 2, v7
	v_and_or_b32 v11, v7, s6, v11
	v_lshl_add_u32 v132, v7, 12, v8
	v_add_u32_e32 v7, 0x2000, v6
	v_ashrrev_i32_e32 v6, 31, v7
	v_lshrrev_b32_e32 v6, 22, v6
	v_and_b32_e32 v9, 24, v9
	v_and_b32_e32 v10, 4, v10
	v_add_u32_e32 v6, v7, v6
	v_or3_b32 v9, v11, v10, v9
	v_ashrrev_i32_e32 v6, 10, v6
	s_load_dwordx2 s[4:5], s[0:1], 0x98
	v_lshl_add_u32 v133, v9, 12, v8
	v_mul_i32_i24_e32 v8, 0x400, v6
	v_sub_u32_e32 v7, v7, v8
	v_lshrrev_b32_e32 v8, 4, v7
	v_bitop3_b32 v8, v8, v7, 32 bitop3:0x6c
	v_lshlrev_b32_e32 v7, 3, v6
	v_and_b32_e32 v9, -16, v7
	v_ashrrev_i32_e32 v7, 31, v8
	s_waitcnt lgkmcnt(0)
	s_add_u32 s0, s4, 0x5a700000
	v_lshrrev_b32_e32 v7, 26, v7
	s_addc_u32 s1, s5, 0
	v_add_u32_e32 v10, v8, v7
	s_add_u32 s2, s4, 0xb900000
	v_ashrrev_i32_e32 v7, 6, v10
	s_addc_u32 s3, s5, 0
	v_add_u32_e32 v9, v7, v9
	v_and_b32_e32 v13, 3, v7
	s_ashr_i32 s16, s14, 31
	v_and_or_b32 v13, v9, s6, v13
	s_lshr_b32 s6, s16, 29
	s_add_i32 s6, s14, s6
	s_ashr_i32 s11, s10, 6
	s_ashr_i32 s7, s6, 3
	s_and_b32 s6, s6, -8
	s_ashr_i32 s13, s10, 8
	s_lshl_b32 s35, s11, 10
	s_sub_i32 s6, s14, s6
	s_cmp_lt_i32 s6, 0
	s_movk_i32 s8, 0xc1
	s_cselect_b32 s8, s8, 0xc0
	s_mul_i32 s6, s6, s8
	s_add_i32 s6, s6, s7
	s_ashr_i32 s7, s6, 31
	s_lshr_b32 s7, s7, 27
	s_add_i32 s7, s6, s7
	s_ashr_i32 s8, s7, 5
	s_and_b32 s7, s7, 0xffe0
	s_sub_i32 s6, s6, s7
	s_bfe_i32 s7, s6, 0x80000
	s_bfe_u32 s7, s7, 0x2000d
	v_and_b32_e32 v10, 0xc0, v10
	s_add_i32 s7, s6, s7
	v_sub_u32_e32 v8, v8, v10
	s_bfe_i32 s9, s7, 0x80000
	v_lshlrev_b32_e32 v11, 5, v6
	v_ashrrev_i16_sdwa v8, v1, sext(v8) dst_sel:DWORD dst_unused:UNUSED_PAD src0_sel:DWORD src1_sel:BYTE_0
	v_lshlrev_b32_e32 v10, 1, v9
	v_lshrrev_b32_e32 v12, 2, v9
	s_sext_i32_i16 s9, s9
	v_and_b32_e32 v11, 32, v11
	v_bfe_i32 v8, v8, 0, 16
	v_and_b32_e32 v10, 24, v10
	v_and_b32_e32 v12, 4, v12
	s_and_b32 s7, s7, 0xfc
	s_ashr_i32 s41, s9, 2
	s_add_i32 s17, s12, 0x10000
	v_or3_b32 v10, v13, v12, v10
	v_add_lshl_u32 v11, v11, v8, 1
	s_sub_i32 s6, s6, s7
	s_lshl_b32 s45, s41, 20
	s_add_i32 s18, s17, s35
	v_lshl_add_u32 v134, v9, 12, v11
	v_lshl_add_u32 v135, v10, 12, v11
	s_lshl_b32 s8, s8, 2
	s_sext_i32_i8 s6, s6
	v_add_u32_e32 v9, s45, v133
	s_mov_b32 m0, s18
	s_add_i32 s19, s18, 0x2000
	s_add_i32 s20, s12, 0x14000
	s_add_i32 s42, s8, s6
	s_sub_i32 s42, 0xbf, s42
	global_load_lds_dwordx4 v9, s[2:3]
	v_add_u32_e32 v9, s45, v135
	s_mov_b32 m0, s19
	s_or_b32 s6, s45, 0x80000
	s_add_i32 s21, s20, s35
	global_load_lds_dwordx4 v9, s[2:3]
	v_add_u32_e32 v9, s6, v133
	s_mov_b32 m0, s21
	s_add_i32 s22, s21, 0x2000
	global_load_lds_dwordx4 v9, s[2:3]
	v_add_u32_e32 v9, s6, v135
	s_mov_b32 m0, s22
	s_lshl_b32 s46, s42, 20
	s_add_i32 s23, s12, s35
	global_load_lds_dwordx4 v9, s[2:3]
	v_add_u32_e32 v9, s46, v132
	s_mov_b32 m0, s23
	s_add_i32 s24, s23, 0x2000
	global_load_lds_dwordx4 v9, s[0:1]
	v_add_u32_e32 v9, s46, v134
	s_mov_b32 m0, s24
	s_or_b32 s6, s46, 0x80000
	s_add_i32 s25, s23, 0x4000
	global_load_lds_dwordx4 v9, s[0:1]
	v_add_u32_e32 v9, s6, v132
	s_mov_b32 m0, s25
	s_add_i32 s26, s23, 0x6000
	global_load_lds_dwordx4 v9, s[0:1]
	v_add_u32_e32 v9, s6, v134
	s_mov_b32 m0, s26
	s_cmp_eq_u32 s13, 1
	global_load_lds_dwordx4 v9, s[0:1]
	s_cselect_b64 s[6:7], -1, 0
	s_cmp_lg_u32 s13, 1
	s_cbranch_scc1 .LBB0_610
	s_barrier

.LBB0_613:
	s_add_i32 s38, s38, 1
	s_mul_i32 s4, s38, s37
	s_mul_hi_u32 s5, s38, s15
	s_add_i32 s5, s5, s4
	s_mul_i32 s4, s38, s15
	s_add_u32 s12, s4, s14
	s_addc_u32 s13, s5, s16
	v_cmp_gt_i64_e32 vcc, s[12:13], v[208:209]
	v_cmp_lt_i64_e64 s[4:5], s[12:13], v[210:211]
	s_cbranch_vccnz .LBB0_615
	s_ashr_i32 s13, s12, 31
	s_lshr_b32 s13, s13, 29
	s_add_i32 s13, s12, s13
	s_ashr_i32 s39, s13, 3
	s_and_b32 s13, s13, -8
	s_sub_i32 s12, s12, s13
	s_cmp_lt_i32 s12, 0
	s_movk_i32 s13, 0xc1
	s_cselect_b32 s13, s13, 0xc0
	s_mul_i32 s12, s12, s13
	s_add_i32 s12, s12, s39
	s_ashr_i32 s13, s12, 31
	s_lshr_b32 s13, s13, 27
	s_add_i32 s13, s12, s13
	s_ashr_i32 s39, s13, 5
	s_lshl_b32 s40, s39, 2
	s_sub_i32 s39, 0xc0, s40
	s_min_i32 s43, s39, 4
	s_abs_i32 s39, s43
	v_cvt_f32_u32_e32 v2, s39
	s_sub_i32 s47, 0, s39
	s_andn2_b32 s13, s13, 31
	s_sub_i32 s12, s12, s13
	v_rcp_iflag_f32_e32 v2, v2
	s_abs_i32 s13, s12
	s_xor_b32 s44, s12, s43
	s_ashr_i32 s44, s44, 31
	v_mul_f32_e32 v2, 0x4f7ffffe, v2
	v_cvt_u32_f32_e32 v2, v2
	s_nop 0
	v_readfirstlane_b32 s48, v2
	s_mul_i32 s47, s47, s48
	s_mul_hi_u32 s47, s48, s47
	s_add_i32 s48, s48, s47
	s_mul_hi_u32 s47, s13, s48
	s_mul_i32 s48, s47, s39
	s_sub_i32 s13, s13, s48
	s_add_i32 s49, s47, 1
	s_sub_i32 s48, s13, s39
	s_cmp_ge_u32 s13, s39
	s_cselect_b32 s47, s49, s47
	s_cselect_b32 s13, s48, s13
	s_add_i32 s48, s47, 1
	s_cmp_ge_u32 s13, s39
	s_cselect_b32 s13, s48, s47
	s_xor_b32 s13, s13, s44
	s_sub_i32 s39, s13, s44
	s_mul_i32 s13, s39, s43
	s_sub_i32 s12, s12, s13
	s_add_i32 s40, s40, s12
	s_sub_i32 s40, 0xbf, s40

	.amdhsa_kernel _Z3fwd4Args
		.amdhsa_group_segment_fixed_size 0
		.amdhsa_private_segment_fixed_size 0
		.amdhsa_kernarg_size 424
		.amdhsa_user_sgpr_count 2
		.amdhsa_user_sgpr_dispatch_ptr 0
		.amdhsa_user_sgpr_queue_ptr 0
		.amdhsa_user_sgpr_kernarg_segment_ptr 1
		.amdhsa_user_sgpr_dispatch_id 0
		.amdhsa_user_sgpr_kernarg_preload_length 0
		.amdhsa_user_sgpr_kernarg_preload_offset 0
		.amdhsa_user_sgpr_private_segment_size 0
		.amdhsa_uses_dynamic_stack 0
		.amdhsa_enable_private_segment 0
		.amdhsa_system_sgpr_workgroup_id_x 1
		.amdhsa_system_sgpr_workgroup_id_y 0
		.amdhsa_system_sgpr_workgroup_id_z 0
		.amdhsa_system_sgpr_workgroup_info 0
		.amdhsa_system_vgpr_workitem_id 0
		.amdhsa_next_free_vgpr 256
		.amdhsa_next_free_sgpr 102
		.amdhsa_accum_offset 256
		.amdhsa_reserve_vcc 1
		.amdhsa_float_round_mode_32 0
		.amdhsa_float_round_mode_16_64 0
		.amdhsa_float_denorm_mode_32 3
		.amdhsa_float_denorm_mode_16_64 3
		.amdhsa_dx10_clamp 1
		.amdhsa_ieee_mode 1
		.amdhsa_fp16_overflow 0
		.amdhsa_tg_split 0
		.amdhsa_exception_fp_ieee_invalid_op 0
		.amdhsa_exception_fp_denorm_src 0
		.amdhsa_exception_fp_ieee_div_zero 0
		.amdhsa_exception_fp_ieee_overflow 0
		.amdhsa_exception_fp_ieee_underflow 0
		.amdhsa_exception_fp_ieee_inexact 0
		.amdhsa_exception_int_div_zero 0
	.end_amdhsa_kernel

amdhsa.kernels:
  - .agpr_count:     0
    .args:
      - .offset:         0
        .size:           168
        .value_kind:     by_value
      - .offset:         168
        .size:           4
        .value_kind:     hidden_block_count_x
      - .offset:         172
        .size:           4
        .value_kind:     hidden_block_count_y
      - .offset:         176
        .size:           4
        .value_kind:     hidden_block_count_z
      - .offset:         180
        .size:           2
        .value_kind:     hidden_group_size_x
      - .offset:         182
        .size:           2
        .value_kind:     hidden_group_size_y
      - .offset:         184
        .size:           2
        .value_kind:     hidden_group_size_z
      - .offset:         186
        .size:           2
        .value_kind:     hidden_remainder_x
      - .offset:         188
        .size:           2
        .value_kind:     hidden_remainder_y
      - .offset:         190
        .size:           2
        .value_kind:     hidden_remainder_z
      - .offset:         208
        .size:           8
        .value_kind:     hidden_global_offset_x
      - .offset:         216
        .size:           8
        .value_kind:     hidden_global_offset_y
      - .offset:         224
        .size:           8
        .value_kind:     hidden_global_offset_z
      - .offset:         232
        .size:           2
        .value_kind:     hidden_grid_dims
      - .offset:         288
        .size:           4
        .value_kind:     hidden_dynamic_lds_size
    .group_segment_fixed_size: 0
    .kernarg_segment_align: 8
    .kernarg_segment_size: 424
    .language:       OpenCL C
    .language_version:
      - 2
      - 0
    .max_flat_workgroup_size: 512
    .name:           _Z3fwd4Args
    .private_segment_fixed_size: 0
    .sgpr_count:     108
    .sgpr_spill_count: 157
    .symbol:         _Z3fwd4Args.kd
    .uniform_work_group_size: 1
    .uses_dynamic_stack: false
    .vgpr_count:     256
    .vgpr_spill_count: 0
    .wavefront_size: 64
